# hand-written RWKV sample-scan loop (fewer instructions per step, buffer addressing); f32 unchanged
# speedup vs baseline: 1.0104x; 1.0104x over previous
.LBB0_636:
	s_andn2_saveexec_b64 s[10:11], s[16:17]
	s_cbranch_execz .LBB0_676
	v_readlane_b32 s2, v240, 10
	v_readfirstlane_b32 s3, v0
	v_and_b32_e32 v220, 63, v190
	s_lshl_b32 s2, s2, 1
	s_add_i32 s2, s2, s3
	v_and_b32_e32 v221, 15, v220
	v_lshrrev_b32_e32 v222, 4, v220
	v_and_b32_e32 v223, 1, v221
	v_cmp_ne_u32_e64 s[100:101], 0, v223
	s_add_u32 s36, s92, 0x1bc24000
	s_addc_u32 s37, s93, 0
	s_and_b32 s37, s37, 0xffff
	s_mov_b32 s38, 0x10000000
	s_mov_b32 s39, 0x20000
	s_add_u32 s40, s92, 0x17c24000
	s_addc_u32 s41, s93, 0
	s_and_b32 s41, s41, 0xffff
	s_mov_b32 s42, 0x10000000
	s_mov_b32 s43, 0x20000
	s_add_u32 s44, s92, 0x1fc24000
	s_addc_u32 s45, s93, 0
	s_and_b32 s45, s45, 0xffff
	s_mov_b32 s46, 0x10000000
	s_mov_b32 s47, 0x20000
	s_add_u32 s48, s92, 0x23c24000
	s_addc_u32 s49, s93, 0
	s_and_b32 s49, s49, 0xffff
	s_mov_b32 s50, 0x10000000
	s_mov_b32 s51, 0x20000
	s_add_u32 s4, s92, 0x2bc24000
	s_addc_u32 s5, s93, 0
	s_and_b32 s5, s5, 0xffff
	s_mov_b32 s6, 0x10000000
	s_mov_b32 s7, 0x20000
	s_add_u32 s16, s92, 0x33c24000
	s_addc_u32 s17, s93, 0
	s_and_b32 s17, s17, 0xffff
	s_mov_b32 s18, 0x10000000
	s_mov_b32 s19, 0x20000
	s_mov_b32 s20, s90
	s_mov_b32 s21, s91
	s_and_b32 s21, s21, 0xffff
	s_mov_b32 s22, 0x10000000
	s_mov_b32 s23, 0x20000
.Lss_item:
	s_cmpk_lt_i32 s2, 0x200
	s_cbranch_scc0 .Lss_done
	s_and_b32 s3, s2, 7
	s_lshr_b32 s99, s2, 3
	s_bfe_u32 s98, s99, 0x10004
	s_lshr_b32 s25, s99, 5
	s_and_b32 s99, s99, 15
	s_lshl_b32 s24, s25, 1
	s_add_i32 s24, s24, s98
	s_lshl_b32 s24, s24, 4
	s_add_i32 s24, s24, s99
	s_lshl_b32 s24, s24, 14
	v_readlane_b32 s8, v241, 27
	v_readlane_b32 s9, v241, 28
	s_add_u32 s8, s8, s24
	s_addc_u32 s9, s9, 0
	s_lshl_b32 s24, s3, 11
	v_lshlrev_b32_e32 v220, 9, v222
	v_lshl_add_u32 v220, v221, 4, v220
	v_add_u32_e32 v220, s24, v220
	s_nop 0
	global_load_dwordx4 v[176:179], v220, s[8:9]
	global_load_dwordx4 v[180:183], v220, s[8:9] offset:256
	s_lshl_b32 s24, s99, 8
	v_lshl_add_u32 v216, v221, 4, s24
	s_lshl_b32 s99, s98, 12
	v_add_u32_e32 v217, s99, v216
	s_lshl_b32 s3, s3, 5
	s_add_i32 s3, s3, s24
	v_lshl_add_u32 v218, v222, 3, s3
	v_lshl_add_u32 v219, v223, 2, v218
	v_add_u32_e32 v219, s99, v219
	s_lshl_b32 s30, s25, 12
	s_addk_i32 s30, 0x2000
	s_mul_i32 s8, s98, 0xfff
	s_add_i32 s30, s30, s8
	s_lshl_b32 s8, s30, 12
	s_lshl_b32 s9, s30, 13
	s_mov_b32 s24, s9
	s_mul_i32 s25, s98, 0xffffe000
	s_addk_i32 s25, 0x1000
	s_lshl_b32 s30, s25, 1
	s_movk_i32 s98, 0x1ff
	buffer_load_dwordx4 v[0:3], v216, s[36:39], s8 offen
	buffer_load_dwordx4 v[12:15], v217, s[16:19], s9 offen
	buffer_load_dwordx2 v[20:21], v218, s[44:47], s8 offen
	buffer_load_dwordx4 v[4:7], v217, s[48:51], s9 offen
	buffer_load_dwordx4 v[8:11], v217, s[4:7], s9 offen
	buffer_load_dwordx4 v[16:19], v216, s[40:43], s8 offen
	s_add_i32 s8, s8, s25
	s_add_i32 s9, s9, s30
	buffer_load_dwordx4 v[22:25], v216, s[36:39], s8 offen
	buffer_load_dwordx4 v[34:37], v217, s[16:19], s9 offen
	buffer_load_dwordx2 v[42:43], v218, s[44:47], s8 offen
	buffer_load_dwordx4 v[26:29], v217, s[48:51], s9 offen
	buffer_load_dwordx4 v[30:33], v217, s[4:7], s9 offen
	buffer_load_dwordx4 v[38:41], v216, s[40:43], s8 offen
	s_add_i32 s8, s8, s25
	s_add_i32 s9, s9, s30
	buffer_load_dwordx4 v[44:47], v216, s[36:39], s8 offen
	buffer_load_dwordx4 v[56:59], v217, s[16:19], s9 offen
	buffer_load_dwordx2 v[64:65], v218, s[44:47], s8 offen
	buffer_load_dwordx4 v[48:51], v217, s[48:51], s9 offen
	buffer_load_dwordx4 v[52:55], v217, s[4:7], s9 offen
	buffer_load_dwordx4 v[60:63], v216, s[40:43], s8 offen
	s_add_i32 s8, s8, s25
	s_add_i32 s9, s9, s30
	buffer_load_dwordx4 v[66:69], v216, s[36:39], s8 offen
	buffer_load_dwordx4 v[78:81], v217, s[16:19], s9 offen
	buffer_load_dwordx2 v[86:87], v218, s[44:47], s8 offen
	buffer_load_dwordx4 v[70:73], v217, s[48:51], s9 offen
	buffer_load_dwordx4 v[74:77], v217, s[4:7], s9 offen
	buffer_load_dwordx4 v[82:85], v216, s[40:43], s8 offen
	s_add_i32 s8, s8, s25
	s_add_i32 s9, s9, s30
	buffer_load_dwordx4 v[88:91], v216, s[36:39], s8 offen
	buffer_load_dwordx4 v[100:103], v217, s[16:19], s9 offen
	buffer_load_dwordx2 v[108:109], v218, s[44:47], s8 offen
	buffer_load_dwordx4 v[92:95], v217, s[48:51], s9 offen
	buffer_load_dwordx4 v[96:99], v217, s[4:7], s9 offen
	buffer_load_dwordx4 v[104:107], v216, s[40:43], s8 offen
	s_add_i32 s8, s8, s25
	s_add_i32 s9, s9, s30
	buffer_load_dwordx4 v[110:113], v216, s[36:39], s8 offen
	buffer_load_dwordx4 v[122:125], v217, s[16:19], s9 offen
	buffer_load_dwordx2 v[130:131], v218, s[44:47], s8 offen
	buffer_load_dwordx4 v[114:117], v217, s[48:51], s9 offen
	buffer_load_dwordx4 v[118:121], v217, s[4:7], s9 offen
	buffer_load_dwordx4 v[126:129], v216, s[40:43], s8 offen
	s_add_i32 s8, s8, s25
	s_add_i32 s9, s9, s30
	buffer_load_dwordx4 v[132:135], v216, s[36:39], s8 offen
	buffer_load_dwordx4 v[144:147], v217, s[16:19], s9 offen
	buffer_load_dwordx2 v[152:153], v218, s[44:47], s8 offen
	buffer_load_dwordx4 v[136:139], v217, s[48:51], s9 offen
	buffer_load_dwordx4 v[140:143], v217, s[4:7], s9 offen
	buffer_load_dwordx4 v[148:151], v216, s[40:43], s8 offen
	s_add_i32 s8, s8, s25
	s_add_i32 s9, s9, s30
	buffer_load_dwordx4 v[154:157], v216, s[36:39], s8 offen
	buffer_load_dwordx4 v[166:169], v217, s[16:19], s9 offen
	buffer_load_dwordx2 v[174:175], v218, s[44:47], s8 offen
	buffer_load_dwordx4 v[158:161], v217, s[48:51], s9 offen
	buffer_load_dwordx4 v[162:165], v217, s[4:7], s9 offen
	buffer_load_dwordx4 v[170:173], v216, s[40:43], s8 offen
	s_add_i32 s8, s8, s25
	s_add_i32 s9, s9, s30
.Lss_loop:
	s_waitcnt vmcnt(42)
	v_pk_mul_f32 v[192:193], v[176:177], v[0:1]
	v_pk_mul_f32 v[194:195], v[180:181], v[0:1]
	v_pk_fma_f32 v[192:193], v[178:179], v[2:3], v[192:193]
	v_pk_fma_f32 v[194:195], v[182:183], v[2:3], v[194:195]
	v_add_f32_e32 v196, v192, v193
	v_add_f32_e32 v197, v194, v195
	v_pk_mul_f32 v[198:199], v[20:21], v[12:13] op_sel_hi:[0,1]
	v_add_f32_dpp v196, v196, v196 quad_perm:[1,0,3,2] row_mask:0xf bank_mask:0xf bound_ctrl:1
	v_add_f32_dpp v197, v197, v197 quad_perm:[1,0,3,2] row_mask:0xf bank_mask:0xf bound_ctrl:1
	v_pk_mul_f32 v[202:203], v[20:21], v[12:13] op_sel:[1,0]
	v_add_f32_dpp v196, v196, v196 quad_perm:[2,3,0,1] row_mask:0xf bank_mask:0xf bound_ctrl:1
	v_add_f32_dpp v197, v197, v197 quad_perm:[2,3,0,1] row_mask:0xf bank_mask:0xf bound_ctrl:1
	v_pk_mul_f32 v[200:201], v[20:21], v[14:15] op_sel_hi:[0,1]
	v_add_f32_dpp v196, v196, v196 row_ror:4 row_mask:0xf bank_mask:0xf bound_ctrl:1
	v_add_f32_dpp v197, v197, v197 row_ror:4 row_mask:0xf bank_mask:0xf bound_ctrl:1
	v_pk_mul_f32 v[204:205], v[20:21], v[14:15] op_sel:[1,0]
	v_add_f32_dpp v196, v196, v196 row_ror:8 row_mask:0xf bank_mask:0xf bound_ctrl:1
	v_add_f32_dpp v197, v197, v197 row_ror:8 row_mask:0xf bank_mask:0xf bound_ctrl:1
	v_pk_fma_f32 v[198:199], v[176:177], v[4:5], v[198:199]
	v_pk_fma_f32 v[202:203], v[180:181], v[4:5], v[202:203]
	v_pk_fma_f32 v[176:177], v[8:9], v[196:197], v[198:199] op_sel_hi:[1,0,1] neg_lo:[0,1,0] neg_hi:[0,1,0]
	v_pk_fma_f32 v[180:181], v[8:9], v[196:197], v[202:203] op_sel:[0,1,0] neg_lo:[0,1,0] neg_hi:[0,1,0]
	v_pk_fma_f32 v[200:201], v[178:179], v[6:7], v[200:201]
	v_pk_fma_f32 v[204:205], v[182:183], v[6:7], v[204:205]
	v_pk_fma_f32 v[178:179], v[10:11], v[196:197], v[200:201] op_sel_hi:[1,0,1] neg_lo:[0,1,0] neg_hi:[0,1,0]
	v_pk_fma_f32 v[182:183], v[10:11], v[196:197], v[204:205] op_sel:[0,1,0] neg_lo:[0,1,0] neg_hi:[0,1,0]
	v_pk_mul_f32 v[206:207], v[176:177], v[16:17]
	v_pk_mul_f32 v[208:209], v[180:181], v[16:17]
	v_pk_fma_f32 v[206:207], v[178:179], v[18:19], v[206:207]
	v_pk_fma_f32 v[208:209], v[182:183], v[18:19], v[208:209]
	v_add_f32_e32 v210, v206, v207
	v_add_f32_e32 v211, v208, v209
	v_cndmask_b32_e64 v212, v210, v211, s[100:101]
	v_cndmask_b32_e64 v213, v211, v210, s[100:101]
	buffer_load_dwordx4 v[0:3], v216, s[36:39], s8 offen
	buffer_load_dwordx4 v[12:15], v217, s[16:19], s9 offen
	v_add_f32_dpp v212, v213, v212 quad_perm:[1,0,3,2] row_mask:0xf bank_mask:0xf bound_ctrl:1
	buffer_load_dwordx2 v[20:21], v218, s[44:47], s8 offen
	buffer_load_dwordx4 v[4:7], v217, s[48:51], s9 offen
	v_add_f32_dpp v212, v212, v212 quad_perm:[2,3,0,1] row_mask:0xf bank_mask:0xf bound_ctrl:1
	buffer_load_dwordx4 v[8:11], v217, s[4:7], s9 offen
	buffer_load_dwordx4 v[16:19], v216, s[40:43], s8 offen
	v_add_f32_dpp v212, v212, v212 row_ror:4 row_mask:0xf bank_mask:0xf bound_ctrl:1
	s_add_i32 s8, s8, s25
	s_add_i32 s9, s9, s30
	v_add_f32_dpp v212, v212, v212 row_ror:8 row_mask:0xf bank_mask:0xf bound_ctrl:1
	buffer_store_dword v212, v219, s[20:23], s24 offen
	s_waitcnt vmcnt(43)
	v_pk_mul_f32 v[192:193], v[176:177], v[22:23]
	v_pk_mul_f32 v[194:195], v[180:181], v[22:23]
	v_pk_fma_f32 v[192:193], v[178:179], v[24:25], v[192:193]
	v_pk_fma_f32 v[194:195], v[182:183], v[24:25], v[194:195]
	v_add_f32_e32 v196, v192, v193
	v_add_f32_e32 v197, v194, v195
	v_pk_mul_f32 v[198:199], v[42:43], v[34:35] op_sel_hi:[0,1]
	v_add_f32_dpp v196, v196, v196 quad_perm:[1,0,3,2] row_mask:0xf bank_mask:0xf bound_ctrl:1
	v_add_f32_dpp v197, v197, v197 quad_perm:[1,0,3,2] row_mask:0xf bank_mask:0xf bound_ctrl:1
	v_pk_mul_f32 v[202:203], v[42:43], v[34:35] op_sel:[1,0]
	v_add_f32_dpp v196, v196, v196 quad_perm:[2,3,0,1] row_mask:0xf bank_mask:0xf bound_ctrl:1
	v_add_f32_dpp v197, v197, v197 quad_perm:[2,3,0,1] row_mask:0xf bank_mask:0xf bound_ctrl:1
	v_pk_mul_f32 v[200:201], v[42:43], v[36:37] op_sel_hi:[0,1]
	v_add_f32_dpp v196, v196, v196 row_ror:4 row_mask:0xf bank_mask:0xf bound_ctrl:1
	v_add_f32_dpp v197, v197, v197 row_ror:4 row_mask:0xf bank_mask:0xf bound_ctrl:1
	v_pk_mul_f32 v[204:205], v[42:43], v[36:37] op_sel:[1,0]
	v_add_f32_dpp v196, v196, v196 row_ror:8 row_mask:0xf bank_mask:0xf bound_ctrl:1
	v_add_f32_dpp v197, v197, v197 row_ror:8 row_mask:0xf bank_mask:0xf bound_ctrl:1
	v_pk_fma_f32 v[198:199], v[176:177], v[26:27], v[198:199]
	v_pk_fma_f32 v[202:203], v[180:181], v[26:27], v[202:203]
	v_pk_fma_f32 v[176:177], v[30:31], v[196:197], v[198:199] op_sel_hi:[1,0,1] neg_lo:[0,1,0] neg_hi:[0,1,0]
	v_pk_fma_f32 v[180:181], v[30:31], v[196:197], v[202:203] op_sel:[0,1,0] neg_lo:[0,1,0] neg_hi:[0,1,0]
	v_pk_fma_f32 v[200:201], v[178:179], v[28:29], v[200:201]
	v_pk_fma_f32 v[204:205], v[182:183], v[28:29], v[204:205]
	v_pk_fma_f32 v[178:179], v[32:33], v[196:197], v[200:201] op_sel_hi:[1,0,1] neg_lo:[0,1,0] neg_hi:[0,1,0]
	v_pk_fma_f32 v[182:183], v[32:33], v[196:197], v[204:205] op_sel:[0,1,0] neg_lo:[0,1,0] neg_hi:[0,1,0]
	v_pk_mul_f32 v[206:207], v[176:177], v[38:39]
	v_pk_mul_f32 v[208:209], v[180:181], v[38:39]
	v_pk_fma_f32 v[206:207], v[178:179], v[40:41], v[206:207]
	v_pk_fma_f32 v[208:209], v[182:183], v[40:41], v[208:209]
	v_add_f32_e32 v210, v206, v207
	v_add_f32_e32 v211, v208, v209
	v_cndmask_b32_e64 v212, v210, v211, s[100:101]
	v_cndmask_b32_e64 v213, v211, v210, s[100:101]
	buffer_load_dwordx4 v[22:25], v216, s[36:39], s8 offen
	buffer_load_dwordx4 v[34:37], v217, s[16:19], s9 offen
	v_add_f32_dpp v212, v213, v212 quad_perm:[1,0,3,2] row_mask:0xf bank_mask:0xf bound_ctrl:1
	s_add_i32 s24, s24, s30
	buffer_load_dwordx2 v[42:43], v218, s[44:47], s8 offen
	v_add_f32_dpp v212, v212, v212 quad_perm:[2,3,0,1] row_mask:0xf bank_mask:0xf bound_ctrl:1
	buffer_load_dwordx4 v[26:29], v217, s[48:51], s9 offen
	buffer_load_dwordx4 v[30:33], v217, s[4:7], s9 offen
	v_add_f32_dpp v212, v212, v212 row_ror:4 row_mask:0xf bank_mask:0xf bound_ctrl:1
	buffer_load_dwordx4 v[38:41], v216, s[40:43], s8 offen
	s_add_i32 s8, s8, s25
	v_add_f32_dpp v212, v212, v212 row_ror:8 row_mask:0xf bank_mask:0xf bound_ctrl:1
	buffer_store_dword v212, v219, s[20:23], s24 offen
	s_waitcnt vmcnt(44)
	v_pk_mul_f32 v[192:193], v[176:177], v[44:45]
	v_pk_mul_f32 v[194:195], v[180:181], v[44:45]
	v_pk_fma_f32 v[192:193], v[178:179], v[46:47], v[192:193]
	v_pk_fma_f32 v[194:195], v[182:183], v[46:47], v[194:195]
	v_add_f32_e32 v196, v192, v193
	v_add_f32_e32 v197, v194, v195
	v_pk_mul_f32 v[198:199], v[64:65], v[56:57] op_sel_hi:[0,1]
	v_add_f32_dpp v196, v196, v196 quad_perm:[1,0,3,2] row_mask:0xf bank_mask:0xf bound_ctrl:1
	v_add_f32_dpp v197, v197, v197 quad_perm:[1,0,3,2] row_mask:0xf bank_mask:0xf bound_ctrl:1
	v_pk_mul_f32 v[202:203], v[64:65], v[56:57] op_sel:[1,0]
	v_add_f32_dpp v196, v196, v196 quad_perm:[2,3,0,1] row_mask:0xf bank_mask:0xf bound_ctrl:1
	v_add_f32_dpp v197, v197, v197 quad_perm:[2,3,0,1] row_mask:0xf bank_mask:0xf bound_ctrl:1
	v_pk_mul_f32 v[200:201], v[64:65], v[58:59] op_sel_hi:[0,1]
	v_add_f32_dpp v196, v196, v196 row_ror:4 row_mask:0xf bank_mask:0xf bound_ctrl:1
	v_add_f32_dpp v197, v197, v197 row_ror:4 row_mask:0xf bank_mask:0xf bound_ctrl:1
	v_pk_mul_f32 v[204:205], v[64:65], v[58:59] op_sel:[1,0]
	v_add_f32_dpp v196, v196, v196 row_ror:8 row_mask:0xf bank_mask:0xf bound_ctrl:1
	v_add_f32_dpp v197, v197, v197 row_ror:8 row_mask:0xf bank_mask:0xf bound_ctrl:1
	v_pk_fma_f32 v[198:199], v[176:177], v[48:49], v[198:199]
	v_pk_fma_f32 v[202:203], v[180:181], v[48:49], v[202:203]
	v_pk_fma_f32 v[176:177], v[52:53], v[196:197], v[198:199] op_sel_hi:[1,0,1] neg_lo:[0,1,0] neg_hi:[0,1,0]
	v_pk_fma_f32 v[180:181], v[52:53], v[196:197], v[202:203] op_sel:[0,1,0] neg_lo:[0,1,0] neg_hi:[0,1,0]
	v_pk_fma_f32 v[200:201], v[178:179], v[50:51], v[200:201]
	v_pk_fma_f32 v[204:205], v[182:183], v[50:51], v[204:205]
	v_pk_fma_f32 v[178:179], v[54:55], v[196:197], v[200:201] op_sel_hi:[1,0,1] neg_lo:[0,1,0] neg_hi:[0,1,0]
	v_pk_fma_f32 v[182:183], v[54:55], v[196:197], v[204:205] op_sel:[0,1,0] neg_lo:[0,1,0] neg_hi:[0,1,0]
	v_pk_mul_f32 v[206:207], v[176:177], v[60:61]
	v_pk_mul_f32 v[208:209], v[180:181], v[60:61]
	v_pk_fma_f32 v[206:207], v[178:179], v[62:63], v[206:207]
	v_pk_fma_f32 v[208:209], v[182:183], v[62:63], v[208:209]
	v_add_f32_e32 v210, v206, v207
	v_add_f32_e32 v211, v208, v209
	v_cndmask_b32_e64 v212, v210, v211, s[100:101]
	v_cndmask_b32_e64 v213, v211, v210, s[100:101]
	s_add_i32 s9, s9, s30
	buffer_load_dwordx4 v[44:47], v216, s[36:39], s8 offen
	v_add_f32_dpp v212, v213, v212 quad_perm:[1,0,3,2] row_mask:0xf bank_mask:0xf bound_ctrl:1
	buffer_load_dwordx4 v[56:59], v217, s[16:19], s9 offen
	s_add_i32 s24, s24, s30
	v_add_f32_dpp v212, v212, v212 quad_perm:[2,3,0,1] row_mask:0xf bank_mask:0xf bound_ctrl:1
	buffer_load_dwordx2 v[64:65], v218, s[44:47], s8 offen
	buffer_load_dwordx4 v[48:51], v217, s[48:51], s9 offen
	v_add_f32_dpp v212, v212, v212 row_ror:4 row_mask:0xf bank_mask:0xf bound_ctrl:1
	buffer_load_dwordx4 v[52:55], v217, s[4:7], s9 offen
	buffer_load_dwordx4 v[60:63], v216, s[40:43], s8 offen
	v_add_f32_dpp v212, v212, v212 row_ror:8 row_mask:0xf bank_mask:0xf bound_ctrl:1
	buffer_store_dword v212, v219, s[20:23], s24 offen
	s_waitcnt vmcnt(45)
	v_pk_mul_f32 v[192:193], v[176:177], v[66:67]
	v_pk_mul_f32 v[194:195], v[180:181], v[66:67]
	v_pk_fma_f32 v[192:193], v[178:179], v[68:69], v[192:193]
	v_pk_fma_f32 v[194:195], v[182:183], v[68:69], v[194:195]
	v_add_f32_e32 v196, v192, v193
	v_add_f32_e32 v197, v194, v195
	v_pk_mul_f32 v[198:199], v[86:87], v[78:79] op_sel_hi:[0,1]
	v_add_f32_dpp v196, v196, v196 quad_perm:[1,0,3,2] row_mask:0xf bank_mask:0xf bound_ctrl:1
	v_add_f32_dpp v197, v197, v197 quad_perm:[1,0,3,2] row_mask:0xf bank_mask:0xf bound_ctrl:1
	v_pk_mul_f32 v[202:203], v[86:87], v[78:79] op_sel:[1,0]
	v_add_f32_dpp v196, v196, v196 quad_perm:[2,3,0,1] row_mask:0xf bank_mask:0xf bound_ctrl:1
	v_add_f32_dpp v197, v197, v197 quad_perm:[2,3,0,1] row_mask:0xf bank_mask:0xf bound_ctrl:1
	v_pk_mul_f32 v[200:201], v[86:87], v[80:81] op_sel_hi:[0,1]
	v_add_f32_dpp v196, v196, v196 row_ror:4 row_mask:0xf bank_mask:0xf bound_ctrl:1
	v_add_f32_dpp v197, v197, v197 row_ror:4 row_mask:0xf bank_mask:0xf bound_ctrl:1
	v_pk_mul_f32 v[204:205], v[86:87], v[80:81] op_sel:[1,0]
	v_add_f32_dpp v196, v196, v196 row_ror:8 row_mask:0xf bank_mask:0xf bound_ctrl:1
	v_add_f32_dpp v197, v197, v197 row_ror:8 row_mask:0xf bank_mask:0xf bound_ctrl:1
	v_pk_fma_f32 v[198:199], v[176:177], v[70:71], v[198:199]
	v_pk_fma_f32 v[202:203], v[180:181], v[70:71], v[202:203]
	v_pk_fma_f32 v[176:177], v[74:75], v[196:197], v[198:199] op_sel_hi:[1,0,1] neg_lo:[0,1,0] neg_hi:[0,1,0]
	v_pk_fma_f32 v[180:181], v[74:75], v[196:197], v[202:203] op_sel:[0,1,0] neg_lo:[0,1,0] neg_hi:[0,1,0]
	v_pk_fma_f32 v[200:201], v[178:179], v[72:73], v[200:201]
	v_pk_fma_f32 v[204:205], v[182:183], v[72:73], v[204:205]
	v_pk_fma_f32 v[178:179], v[76:77], v[196:197], v[200:201] op_sel_hi:[1,0,1] neg_lo:[0,1,0] neg_hi:[0,1,0]
	v_pk_fma_f32 v[182:183], v[76:77], v[196:197], v[204:205] op_sel:[0,1,0] neg_lo:[0,1,0] neg_hi:[0,1,0]
	v_pk_mul_f32 v[206:207], v[176:177], v[82:83]
	v_pk_mul_f32 v[208:209], v[180:181], v[82:83]
	v_pk_fma_f32 v[206:207], v[178:179], v[84:85], v[206:207]
	v_pk_fma_f32 v[208:209], v[182:183], v[84:85], v[208:209]
	v_add_f32_e32 v210, v206, v207
	v_add_f32_e32 v211, v208, v209
	v_cndmask_b32_e64 v212, v210, v211, s[100:101]
	v_cndmask_b32_e64 v213, v211, v210, s[100:101]
	s_add_i32 s8, s8, s25
	s_add_i32 s9, s9, s30
	v_add_f32_dpp v212, v213, v212 quad_perm:[1,0,3,2] row_mask:0xf bank_mask:0xf bound_ctrl:1
	buffer_load_dwordx4 v[66:69], v216, s[36:39], s8 offen
	buffer_load_dwordx4 v[78:81], v217, s[16:19], s9 offen
	v_add_f32_dpp v212, v212, v212 quad_perm:[2,3,0,1] row_mask:0xf bank_mask:0xf bound_ctrl:1
	s_add_i32 s24, s24, s30
	buffer_load_dwordx2 v[86:87], v218, s[44:47], s8 offen
	v_add_f32_dpp v212, v212, v212 row_ror:4 row_mask:0xf bank_mask:0xf bound_ctrl:1
	buffer_load_dwordx4 v[70:73], v217, s[48:51], s9 offen
	buffer_load_dwordx4 v[74:77], v217, s[4:7], s9 offen
	v_add_f32_dpp v212, v212, v212 row_ror:8 row_mask:0xf bank_mask:0xf bound_ctrl:1
	buffer_load_dwordx4 v[82:85], v216, s[40:43], s8 offen
	buffer_store_dword v212, v219, s[20:23], s24 offen
	s_waitcnt vmcnt(46)
	v_pk_mul_f32 v[192:193], v[176:177], v[88:89]
	v_pk_mul_f32 v[194:195], v[180:181], v[88:89]
	v_pk_fma_f32 v[192:193], v[178:179], v[90:91], v[192:193]
	v_pk_fma_f32 v[194:195], v[182:183], v[90:91], v[194:195]
	v_add_f32_e32 v196, v192, v193
	v_add_f32_e32 v197, v194, v195
	v_pk_mul_f32 v[198:199], v[108:109], v[100:101] op_sel_hi:[0,1]
	v_add_f32_dpp v196, v196, v196 quad_perm:[1,0,3,2] row_mask:0xf bank_mask:0xf bound_ctrl:1
	v_add_f32_dpp v197, v197, v197 quad_perm:[1,0,3,2] row_mask:0xf bank_mask:0xf bound_ctrl:1
	v_pk_mul_f32 v[202:203], v[108:109], v[100:101] op_sel:[1,0]
	v_add_f32_dpp v196, v196, v196 quad_perm:[2,3,0,1] row_mask:0xf bank_mask:0xf bound_ctrl:1
	v_add_f32_dpp v197, v197, v197 quad_perm:[2,3,0,1] row_mask:0xf bank_mask:0xf bound_ctrl:1
	v_pk_mul_f32 v[200:201], v[108:109], v[102:103] op_sel_hi:[0,1]
	v_add_f32_dpp v196, v196, v196 row_ror:4 row_mask:0xf bank_mask:0xf bound_ctrl:1
	v_add_f32_dpp v197, v197, v197 row_ror:4 row_mask:0xf bank_mask:0xf bound_ctrl:1
	v_pk_mul_f32 v[204:205], v[108:109], v[102:103] op_sel:[1,0]
	v_add_f32_dpp v196, v196, v196 row_ror:8 row_mask:0xf bank_mask:0xf bound_ctrl:1
	v_add_f32_dpp v197, v197, v197 row_ror:8 row_mask:0xf bank_mask:0xf bound_ctrl:1
	v_pk_fma_f32 v[198:199], v[176:177], v[92:93], v[198:199]
	v_pk_fma_f32 v[202:203], v[180:181], v[92:93], v[202:203]
	v_pk_fma_f32 v[176:177], v[96:97], v[196:197], v[198:199] op_sel_hi:[1,0,1] neg_lo:[0,1,0] neg_hi:[0,1,0]
	v_pk_fma_f32 v[180:181], v[96:97], v[196:197], v[202:203] op_sel:[0,1,0] neg_lo:[0,1,0] neg_hi:[0,1,0]
	v_pk_fma_f32 v[200:201], v[178:179], v[94:95], v[200:201]
	v_pk_fma_f32 v[204:205], v[182:183], v[94:95], v[204:205]
	v_pk_fma_f32 v[178:179], v[98:99], v[196:197], v[200:201] op_sel_hi:[1,0,1] neg_lo:[0,1,0] neg_hi:[0,1,0]
	v_pk_fma_f32 v[182:183], v[98:99], v[196:197], v[204:205] op_sel:[0,1,0] neg_lo:[0,1,0] neg_hi:[0,1,0]
	v_pk_mul_f32 v[206:207], v[176:177], v[104:105]
	v_pk_mul_f32 v[208:209], v[180:181], v[104:105]
	v_pk_fma_f32 v[206:207], v[178:179], v[106:107], v[206:207]
	v_pk_fma_f32 v[208:209], v[182:183], v[106:107], v[208:209]
	v_add_f32_e32 v210, v206, v207
	v_add_f32_e32 v211, v208, v209
	v_cndmask_b32_e64 v212, v210, v211, s[100:101]
	v_cndmask_b32_e64 v213, v211, v210, s[100:101]
	s_add_i32 s8, s8, s25
	s_add_i32 s9, s9, s30
	v_add_f32_dpp v212, v213, v212 quad_perm:[1,0,3,2] row_mask:0xf bank_mask:0xf bound_ctrl:1
	buffer_load_dwordx4 v[88:91], v216, s[36:39], s8 offen
	buffer_load_dwordx4 v[100:103], v217, s[16:19], s9 offen
	v_add_f32_dpp v212, v212, v212 quad_perm:[2,3,0,1] row_mask:0xf bank_mask:0xf bound_ctrl:1
	s_add_i32 s24, s24, s30
	buffer_load_dwordx2 v[108:109], v218, s[44:47], s8 offen
	v_add_f32_dpp v212, v212, v212 row_ror:4 row_mask:0xf bank_mask:0xf bound_ctrl:1
	buffer_load_dwordx4 v[92:95], v217, s[48:51], s9 offen
	buffer_load_dwordx4 v[96:99], v217, s[4:7], s9 offen
	v_add_f32_dpp v212, v212, v212 row_ror:8 row_mask:0xf bank_mask:0xf bound_ctrl:1
	buffer_load_dwordx4 v[104:107], v216, s[40:43], s8 offen
	buffer_store_dword v212, v219, s[20:23], s24 offen
	s_waitcnt vmcnt(47)
	v_pk_mul_f32 v[192:193], v[176:177], v[110:111]
	v_pk_mul_f32 v[194:195], v[180:181], v[110:111]
	v_pk_fma_f32 v[192:193], v[178:179], v[112:113], v[192:193]
	v_pk_fma_f32 v[194:195], v[182:183], v[112:113], v[194:195]
	v_add_f32_e32 v196, v192, v193
	v_add_f32_e32 v197, v194, v195
	v_pk_mul_f32 v[198:199], v[130:131], v[122:123] op_sel_hi:[0,1]
	v_add_f32_dpp v196, v196, v196 quad_perm:[1,0,3,2] row_mask:0xf bank_mask:0xf bound_ctrl:1
	v_add_f32_dpp v197, v197, v197 quad_perm:[1,0,3,2] row_mask:0xf bank_mask:0xf bound_ctrl:1
	v_pk_mul_f32 v[202:203], v[130:131], v[122:123] op_sel:[1,0]
	v_add_f32_dpp v196, v196, v196 quad_perm:[2,3,0,1] row_mask:0xf bank_mask:0xf bound_ctrl:1
	v_add_f32_dpp v197, v197, v197 quad_perm:[2,3,0,1] row_mask:0xf bank_mask:0xf bound_ctrl:1
	v_pk_mul_f32 v[200:201], v[130:131], v[124:125] op_sel_hi:[0,1]
	v_add_f32_dpp v196, v196, v196 row_ror:4 row_mask:0xf bank_mask:0xf bound_ctrl:1
	v_add_f32_dpp v197, v197, v197 row_ror:4 row_mask:0xf bank_mask:0xf bound_ctrl:1
	v_pk_mul_f32 v[204:205], v[130:131], v[124:125] op_sel:[1,0]
	v_add_f32_dpp v196, v196, v196 row_ror:8 row_mask:0xf bank_mask:0xf bound_ctrl:1
	v_add_f32_dpp v197, v197, v197 row_ror:8 row_mask:0xf bank_mask:0xf bound_ctrl:1
	v_pk_fma_f32 v[198:199], v[176:177], v[114:115], v[198:199]
	v_pk_fma_f32 v[202:203], v[180:181], v[114:115], v[202:203]
	v_pk_fma_f32 v[176:177], v[118:119], v[196:197], v[198:199] op_sel_hi:[1,0,1] neg_lo:[0,1,0] neg_hi:[0,1,0]
	v_pk_fma_f32 v[180:181], v[118:119], v[196:197], v[202:203] op_sel:[0,1,0] neg_lo:[0,1,0] neg_hi:[0,1,0]
	v_pk_fma_f32 v[200:201], v[178:179], v[116:117], v[200:201]
	v_pk_fma_f32 v[204:205], v[182:183], v[116:117], v[204:205]
	v_pk_fma_f32 v[178:179], v[120:121], v[196:197], v[200:201] op_sel_hi:[1,0,1] neg_lo:[0,1,0] neg_hi:[0,1,0]
	v_pk_fma_f32 v[182:183], v[120:121], v[196:197], v[204:205] op_sel:[0,1,0] neg_lo:[0,1,0] neg_hi:[0,1,0]
	v_pk_mul_f32 v[206:207], v[176:177], v[126:127]
	v_pk_mul_f32 v[208:209], v[180:181], v[126:127]
	v_pk_fma_f32 v[206:207], v[178:179], v[128:129], v[206:207]
	v_pk_fma_f32 v[208:209], v[182:183], v[128:129], v[208:209]
	v_add_f32_e32 v210, v206, v207
	v_add_f32_e32 v211, v208, v209
	v_cndmask_b32_e64 v212, v210, v211, s[100:101]
	v_cndmask_b32_e64 v213, v211, v210, s[100:101]
	s_add_i32 s8, s8, s25
	s_add_i32 s9, s9, s30
	v_add_f32_dpp v212, v213, v212 quad_perm:[1,0,3,2] row_mask:0xf bank_mask:0xf bound_ctrl:1
	buffer_load_dwordx4 v[110:113], v216, s[36:39], s8 offen
	buffer_load_dwordx4 v[122:125], v217, s[16:19], s9 offen
	v_add_f32_dpp v212, v212, v212 quad_perm:[2,3,0,1] row_mask:0xf bank_mask:0xf bound_ctrl:1
	s_add_i32 s24, s24, s30
	buffer_load_dwordx2 v[130:131], v218, s[44:47], s8 offen
	v_add_f32_dpp v212, v212, v212 row_ror:4 row_mask:0xf bank_mask:0xf bound_ctrl:1
	buffer_load_dwordx4 v[114:117], v217, s[48:51], s9 offen
	buffer_load_dwordx4 v[118:121], v217, s[4:7], s9 offen
	v_add_f32_dpp v212, v212, v212 row_ror:8 row_mask:0xf bank_mask:0xf bound_ctrl:1
	buffer_load_dwordx4 v[126:129], v216, s[40:43], s8 offen
	buffer_store_dword v212, v219, s[20:23], s24 offen
	s_waitcnt vmcnt(48)
	v_pk_mul_f32 v[192:193], v[176:177], v[132:133]
	v_pk_mul_f32 v[194:195], v[180:181], v[132:133]
	v_pk_fma_f32 v[192:193], v[178:179], v[134:135], v[192:193]
	v_pk_fma_f32 v[194:195], v[182:183], v[134:135], v[194:195]
	v_add_f32_e32 v196, v192, v193
	v_add_f32_e32 v197, v194, v195
	v_pk_mul_f32 v[198:199], v[152:153], v[144:145] op_sel_hi:[0,1]
	v_add_f32_dpp v196, v196, v196 quad_perm:[1,0,3,2] row_mask:0xf bank_mask:0xf bound_ctrl:1
	v_add_f32_dpp v197, v197, v197 quad_perm:[1,0,3,2] row_mask:0xf bank_mask:0xf bound_ctrl:1
	v_pk_mul_f32 v[202:203], v[152:153], v[144:145] op_sel:[1,0]
	v_add_f32_dpp v196, v196, v196 quad_perm:[2,3,0,1] row_mask:0xf bank_mask:0xf bound_ctrl:1
	v_add_f32_dpp v197, v197, v197 quad_perm:[2,3,0,1] row_mask:0xf bank_mask:0xf bound_ctrl:1
	v_pk_mul_f32 v[200:201], v[152:153], v[146:147] op_sel_hi:[0,1]
	v_add_f32_dpp v196, v196, v196 row_ror:4 row_mask:0xf bank_mask:0xf bound_ctrl:1
	v_add_f32_dpp v197, v197, v197 row_ror:4 row_mask:0xf bank_mask:0xf bound_ctrl:1
	v_pk_mul_f32 v[204:205], v[152:153], v[146:147] op_sel:[1,0]
	v_add_f32_dpp v196, v196, v196 row_ror:8 row_mask:0xf bank_mask:0xf bound_ctrl:1
	v_add_f32_dpp v197, v197, v197 row_ror:8 row_mask:0xf bank_mask:0xf bound_ctrl:1
	v_pk_fma_f32 v[198:199], v[176:177], v[136:137], v[198:199]
	v_pk_fma_f32 v[202:203], v[180:181], v[136:137], v[202:203]
	v_pk_fma_f32 v[176:177], v[140:141], v[196:197], v[198:199] op_sel_hi:[1,0,1] neg_lo:[0,1,0] neg_hi:[0,1,0]
	v_pk_fma_f32 v[180:181], v[140:141], v[196:197], v[202:203] op_sel:[0,1,0] neg_lo:[0,1,0] neg_hi:[0,1,0]
	v_pk_fma_f32 v[200:201], v[178:179], v[138:139], v[200:201]
	v_pk_fma_f32 v[204:205], v[182:183], v[138:139], v[204:205]
	v_pk_fma_f32 v[178:179], v[142:143], v[196:197], v[200:201] op_sel_hi:[1,0,1] neg_lo:[0,1,0] neg_hi:[0,1,0]
	v_pk_fma_f32 v[182:183], v[142:143], v[196:197], v[204:205] op_sel:[0,1,0] neg_lo:[0,1,0] neg_hi:[0,1,0]
	v_pk_mul_f32 v[206:207], v[176:177], v[148:149]
	v_pk_mul_f32 v[208:209], v[180:181], v[148:149]
	v_pk_fma_f32 v[206:207], v[178:179], v[150:151], v[206:207]
	v_pk_fma_f32 v[208:209], v[182:183], v[150:151], v[208:209]
	v_add_f32_e32 v210, v206, v207
	v_add_f32_e32 v211, v208, v209
	v_cndmask_b32_e64 v212, v210, v211, s[100:101]
	v_cndmask_b32_e64 v213, v211, v210, s[100:101]
	s_add_i32 s8, s8, s25
	s_add_i32 s9, s9, s30
	v_add_f32_dpp v212, v213, v212 quad_perm:[1,0,3,2] row_mask:0xf bank_mask:0xf bound_ctrl:1
	buffer_load_dwordx4 v[132:135], v216, s[36:39], s8 offen
	buffer_load_dwordx4 v[144:147], v217, s[16:19], s9 offen
	v_add_f32_dpp v212, v212, v212 quad_perm:[2,3,0,1] row_mask:0xf bank_mask:0xf bound_ctrl:1
	s_add_i32 s24, s24, s30
	buffer_load_dwordx2 v[152:153], v218, s[44:47], s8 offen
	v_add_f32_dpp v212, v212, v212 row_ror:4 row_mask:0xf bank_mask:0xf bound_ctrl:1
	buffer_load_dwordx4 v[136:139], v217, s[48:51], s9 offen
	buffer_load_dwordx4 v[140:143], v217, s[4:7], s9 offen
	v_add_f32_dpp v212, v212, v212 row_ror:8 row_mask:0xf bank_mask:0xf bound_ctrl:1
	buffer_load_dwordx4 v[148:151], v216, s[40:43], s8 offen
	buffer_store_dword v212, v219, s[20:23], s24 offen
	s_waitcnt vmcnt(49)
	v_pk_mul_f32 v[192:193], v[176:177], v[154:155]
	v_pk_mul_f32 v[194:195], v[180:181], v[154:155]
	v_pk_fma_f32 v[192:193], v[178:179], v[156:157], v[192:193]
	v_pk_fma_f32 v[194:195], v[182:183], v[156:157], v[194:195]
	v_add_f32_e32 v196, v192, v193
	v_add_f32_e32 v197, v194, v195
	v_pk_mul_f32 v[198:199], v[174:175], v[166:167] op_sel_hi:[0,1]
	v_add_f32_dpp v196, v196, v196 quad_perm:[1,0,3,2] row_mask:0xf bank_mask:0xf bound_ctrl:1
	v_add_f32_dpp v197, v197, v197 quad_perm:[1,0,3,2] row_mask:0xf bank_mask:0xf bound_ctrl:1
	v_pk_mul_f32 v[202:203], v[174:175], v[166:167] op_sel:[1,0]
	v_add_f32_dpp v196, v196, v196 quad_perm:[2,3,0,1] row_mask:0xf bank_mask:0xf bound_ctrl:1
	v_add_f32_dpp v197, v197, v197 quad_perm:[2,3,0,1] row_mask:0xf bank_mask:0xf bound_ctrl:1
	v_pk_mul_f32 v[200:201], v[174:175], v[168:169] op_sel_hi:[0,1]
	v_add_f32_dpp v196, v196, v196 row_ror:4 row_mask:0xf bank_mask:0xf bound_ctrl:1
	v_add_f32_dpp v197, v197, v197 row_ror:4 row_mask:0xf bank_mask:0xf bound_ctrl:1
	v_pk_mul_f32 v[204:205], v[174:175], v[168:169] op_sel:[1,0]
	v_add_f32_dpp v196, v196, v196 row_ror:8 row_mask:0xf bank_mask:0xf bound_ctrl:1
	v_add_f32_dpp v197, v197, v197 row_ror:8 row_mask:0xf bank_mask:0xf bound_ctrl:1
	v_pk_fma_f32 v[198:199], v[176:177], v[158:159], v[198:199]
	v_pk_fma_f32 v[202:203], v[180:181], v[158:159], v[202:203]
	v_pk_fma_f32 v[176:177], v[162:163], v[196:197], v[198:199] op_sel_hi:[1,0,1] neg_lo:[0,1,0] neg_hi:[0,1,0]
	v_pk_fma_f32 v[180:181], v[162:163], v[196:197], v[202:203] op_sel:[0,1,0] neg_lo:[0,1,0] neg_hi:[0,1,0]
	v_pk_fma_f32 v[200:201], v[178:179], v[160:161], v[200:201]
	v_pk_fma_f32 v[204:205], v[182:183], v[160:161], v[204:205]
	v_pk_fma_f32 v[178:179], v[164:165], v[196:197], v[200:201] op_sel_hi:[1,0,1] neg_lo:[0,1,0] neg_hi:[0,1,0]
	v_pk_fma_f32 v[182:183], v[164:165], v[196:197], v[204:205] op_sel:[0,1,0] neg_lo:[0,1,0] neg_hi:[0,1,0]
	v_pk_mul_f32 v[206:207], v[176:177], v[170:171]
	v_pk_mul_f32 v[208:209], v[180:181], v[170:171]
	v_pk_fma_f32 v[206:207], v[178:179], v[172:173], v[206:207]
	v_pk_fma_f32 v[208:209], v[182:183], v[172:173], v[208:209]
	v_add_f32_e32 v210, v206, v207
	v_add_f32_e32 v211, v208, v209
	v_cndmask_b32_e64 v212, v210, v211, s[100:101]
	v_cndmask_b32_e64 v213, v211, v210, s[100:101]
	s_add_i32 s8, s8, s25
	s_add_i32 s9, s9, s30
	v_add_f32_dpp v212, v213, v212 quad_perm:[1,0,3,2] row_mask:0xf bank_mask:0xf bound_ctrl:1
	buffer_load_dwordx4 v[154:157], v216, s[36:39], s8 offen
	buffer_load_dwordx4 v[166:169], v217, s[16:19], s9 offen
	v_add_f32_dpp v212, v212, v212 quad_perm:[2,3,0,1] row_mask:0xf bank_mask:0xf bound_ctrl:1
	s_add_i32 s24, s24, s30
	buffer_load_dwordx2 v[174:175], v218, s[44:47], s8 offen
	v_add_f32_dpp v212, v212, v212 row_ror:4 row_mask:0xf bank_mask:0xf bound_ctrl:1
	buffer_load_dwordx4 v[158:161], v217, s[48:51], s9 offen
	buffer_load_dwordx4 v[162:165], v217, s[4:7], s9 offen
	v_add_f32_dpp v212, v212, v212 row_ror:8 row_mask:0xf bank_mask:0xf bound_ctrl:1
	buffer_load_dwordx4 v[170:173], v216, s[40:43], s8 offen
	buffer_store_dword v212, v219, s[20:23], s24 offen
	s_add_i32 s8, s8, s25
	s_add_i32 s9, s9, s30
	s_add_i32 s24, s24, s30
	s_add_i32 s98, s98, -1
	s_cmp_lg_u32 s98, 0
	s_cbranch_scc1 .Lss_loop
	s_waitcnt vmcnt(50)
	v_pk_mul_f32 v[192:193], v[176:177], v[0:1]
	v_pk_mul_f32 v[194:195], v[180:181], v[0:1]
	v_pk_fma_f32 v[192:193], v[178:179], v[2:3], v[192:193]
	v_pk_fma_f32 v[194:195], v[182:183], v[2:3], v[194:195]
	v_add_f32_e32 v196, v192, v193
	v_add_f32_e32 v197, v194, v195
	v_pk_mul_f32 v[198:199], v[20:21], v[12:13] op_sel_hi:[0,1]
	v_add_f32_dpp v196, v196, v196 quad_perm:[1,0,3,2] row_mask:0xf bank_mask:0xf bound_ctrl:1
	v_add_f32_dpp v197, v197, v197 quad_perm:[1,0,3,2] row_mask:0xf bank_mask:0xf bound_ctrl:1
	v_pk_mul_f32 v[202:203], v[20:21], v[12:13] op_sel:[1,0]
	v_add_f32_dpp v196, v196, v196 quad_perm:[2,3,0,1] row_mask:0xf bank_mask:0xf bound_ctrl:1
	v_add_f32_dpp v197, v197, v197 quad_perm:[2,3,0,1] row_mask:0xf bank_mask:0xf bound_ctrl:1
	v_pk_mul_f32 v[200:201], v[20:21], v[14:15] op_sel_hi:[0,1]
	v_add_f32_dpp v196, v196, v196 row_ror:4 row_mask:0xf bank_mask:0xf bound_ctrl:1
	v_add_f32_dpp v197, v197, v197 row_ror:4 row_mask:0xf bank_mask:0xf bound_ctrl:1
	v_pk_mul_f32 v[204:205], v[20:21], v[14:15] op_sel:[1,0]
	v_add_f32_dpp v196, v196, v196 row_ror:8 row_mask:0xf bank_mask:0xf bound_ctrl:1
	v_add_f32_dpp v197, v197, v197 row_ror:8 row_mask:0xf bank_mask:0xf bound_ctrl:1
	v_pk_fma_f32 v[198:199], v[176:177], v[4:5], v[198:199]
	v_pk_fma_f32 v[202:203], v[180:181], v[4:5], v[202:203]
	v_pk_fma_f32 v[176:177], v[8:9], v[196:197], v[198:199] op_sel_hi:[1,0,1] neg_lo:[0,1,0] neg_hi:[0,1,0]
	v_pk_fma_f32 v[180:181], v[8:9], v[196:197], v[202:203] op_sel:[0,1,0] neg_lo:[0,1,0] neg_hi:[0,1,0]
	v_pk_fma_f32 v[200:201], v[178:179], v[6:7], v[200:201]
	v_pk_fma_f32 v[204:205], v[182:183], v[6:7], v[204:205]
	v_pk_fma_f32 v[178:179], v[10:11], v[196:197], v[200:201] op_sel_hi:[1,0,1] neg_lo:[0,1,0] neg_hi:[0,1,0]
	v_pk_fma_f32 v[182:183], v[10:11], v[196:197], v[204:205] op_sel:[0,1,0] neg_lo:[0,1,0] neg_hi:[0,1,0]
	v_pk_mul_f32 v[206:207], v[176:177], v[16:17]
	v_pk_mul_f32 v[208:209], v[180:181], v[16:17]
	v_pk_fma_f32 v[206:207], v[178:179], v[18:19], v[206:207]
	v_pk_fma_f32 v[208:209], v[182:183], v[18:19], v[208:209]
	v_add_f32_e32 v210, v206, v207
	v_add_f32_e32 v211, v208, v209
	v_cndmask_b32_e64 v212, v210, v211, s[100:101]
	v_cndmask_b32_e64 v213, v211, v210, s[100:101]
	s_nop 0
	s_nop 0
	v_add_f32_dpp v212, v213, v212 quad_perm:[1,0,3,2] row_mask:0xf bank_mask:0xf bound_ctrl:1
	s_nop 0
	s_nop 0
	v_add_f32_dpp v212, v212, v212 quad_perm:[2,3,0,1] row_mask:0xf bank_mask:0xf bound_ctrl:1
	s_nop 0
	s_nop 0
	v_add_f32_dpp v212, v212, v212 row_ror:4 row_mask:0xf bank_mask:0xf bound_ctrl:1
	s_nop 0
	s_nop 0
	v_add_f32_dpp v212, v212, v212 row_ror:8 row_mask:0xf bank_mask:0xf bound_ctrl:1
	buffer_store_dword v212, v219, s[20:23], s24 offen
	s_waitcnt vmcnt(44)
	v_pk_mul_f32 v[192:193], v[176:177], v[22:23]
	v_pk_mul_f32 v[194:195], v[180:181], v[22:23]
	v_pk_fma_f32 v[192:193], v[178:179], v[24:25], v[192:193]
	v_pk_fma_f32 v[194:195], v[182:183], v[24:25], v[194:195]
	v_add_f32_e32 v196, v192, v193
	v_add_f32_e32 v197, v194, v195
	v_pk_mul_f32 v[198:199], v[42:43], v[34:35] op_sel_hi:[0,1]
	v_add_f32_dpp v196, v196, v196 quad_perm:[1,0,3,2] row_mask:0xf bank_mask:0xf bound_ctrl:1
	v_add_f32_dpp v197, v197, v197 quad_perm:[1,0,3,2] row_mask:0xf bank_mask:0xf bound_ctrl:1
	v_pk_mul_f32 v[202:203], v[42:43], v[34:35] op_sel:[1,0]
	v_add_f32_dpp v196, v196, v196 quad_perm:[2,3,0,1] row_mask:0xf bank_mask:0xf bound_ctrl:1
	v_add_f32_dpp v197, v197, v197 quad_perm:[2,3,0,1] row_mask:0xf bank_mask:0xf bound_ctrl:1
	v_pk_mul_f32 v[200:201], v[42:43], v[36:37] op_sel_hi:[0,1]
	v_add_f32_dpp v196, v196, v196 row_ror:4 row_mask:0xf bank_mask:0xf bound_ctrl:1
	v_add_f32_dpp v197, v197, v197 row_ror:4 row_mask:0xf bank_mask:0xf bound_ctrl:1
	v_pk_mul_f32 v[204:205], v[42:43], v[36:37] op_sel:[1,0]
	v_add_f32_dpp v196, v196, v196 row_ror:8 row_mask:0xf bank_mask:0xf bound_ctrl:1
	v_add_f32_dpp v197, v197, v197 row_ror:8 row_mask:0xf bank_mask:0xf bound_ctrl:1
	v_pk_fma_f32 v[198:199], v[176:177], v[26:27], v[198:199]
	v_pk_fma_f32 v[202:203], v[180:181], v[26:27], v[202:203]
	v_pk_fma_f32 v[176:177], v[30:31], v[196:197], v[198:199] op_sel_hi:[1,0,1] neg_lo:[0,1,0] neg_hi:[0,1,0]
	v_pk_fma_f32 v[180:181], v[30:31], v[196:197], v[202:203] op_sel:[0,1,0] neg_lo:[0,1,0] neg_hi:[0,1,0]
	v_pk_fma_f32 v[200:201], v[178:179], v[28:29], v[200:201]
	v_pk_fma_f32 v[204:205], v[182:183], v[28:29], v[204:205]
	v_pk_fma_f32 v[178:179], v[32:33], v[196:197], v[200:201] op_sel_hi:[1,0,1] neg_lo:[0,1,0] neg_hi:[0,1,0]
	v_pk_fma_f32 v[182:183], v[32:33], v[196:197], v[204:205] op_sel:[0,1,0] neg_lo:[0,1,0] neg_hi:[0,1,0]
	v_pk_mul_f32 v[206:207], v[176:177], v[38:39]
	v_pk_mul_f32 v[208:209], v[180:181], v[38:39]
	v_pk_fma_f32 v[206:207], v[178:179], v[40:41], v[206:207]
	v_pk_fma_f32 v[208:209], v[182:183], v[40:41], v[208:209]
	v_add_f32_e32 v210, v206, v207
	v_add_f32_e32 v211, v208, v209
	v_cndmask_b32_e64 v212, v210, v211, s[100:101]
	v_cndmask_b32_e64 v213, v211, v210, s[100:101]
	s_add_i32 s24, s24, s30
	s_nop 0
	v_add_f32_dpp v212, v213, v212 quad_perm:[1,0,3,2] row_mask:0xf bank_mask:0xf bound_ctrl:1
	s_nop 0
	s_nop 0
	v_add_f32_dpp v212, v212, v212 quad_perm:[2,3,0,1] row_mask:0xf bank_mask:0xf bound_ctrl:1
	s_nop 0
	s_nop 0
	v_add_f32_dpp v212, v212, v212 row_ror:4 row_mask:0xf bank_mask:0xf bound_ctrl:1
	s_nop 0
	s_nop 0
	v_add_f32_dpp v212, v212, v212 row_ror:8 row_mask:0xf bank_mask:0xf bound_ctrl:1
	buffer_store_dword v212, v219, s[20:23], s24 offen
	s_waitcnt vmcnt(38)
	v_pk_mul_f32 v[192:193], v[176:177], v[44:45]
	v_pk_mul_f32 v[194:195], v[180:181], v[44:45]
	v_pk_fma_f32 v[192:193], v[178:179], v[46:47], v[192:193]
	v_pk_fma_f32 v[194:195], v[182:183], v[46:47], v[194:195]
	v_add_f32_e32 v196, v192, v193
	v_add_f32_e32 v197, v194, v195
	v_pk_mul_f32 v[198:199], v[64:65], v[56:57] op_sel_hi:[0,1]
	v_add_f32_dpp v196, v196, v196 quad_perm:[1,0,3,2] row_mask:0xf bank_mask:0xf bound_ctrl:1
	v_add_f32_dpp v197, v197, v197 quad_perm:[1,0,3,2] row_mask:0xf bank_mask:0xf bound_ctrl:1
	v_pk_mul_f32 v[202:203], v[64:65], v[56:57] op_sel:[1,0]
	v_add_f32_dpp v196, v196, v196 quad_perm:[2,3,0,1] row_mask:0xf bank_mask:0xf bound_ctrl:1
	v_add_f32_dpp v197, v197, v197 quad_perm:[2,3,0,1] row_mask:0xf bank_mask:0xf bound_ctrl:1
	v_pk_mul_f32 v[200:201], v[64:65], v[58:59] op_sel_hi:[0,1]
	v_add_f32_dpp v196, v196, v196 row_ror:4 row_mask:0xf bank_mask:0xf bound_ctrl:1
	v_add_f32_dpp v197, v197, v197 row_ror:4 row_mask:0xf bank_mask:0xf bound_ctrl:1
	v_pk_mul_f32 v[204:205], v[64:65], v[58:59] op_sel:[1,0]
	v_add_f32_dpp v196, v196, v196 row_ror:8 row_mask:0xf bank_mask:0xf bound_ctrl:1
	v_add_f32_dpp v197, v197, v197 row_ror:8 row_mask:0xf bank_mask:0xf bound_ctrl:1
	v_pk_fma_f32 v[198:199], v[176:177], v[48:49], v[198:199]
	v_pk_fma_f32 v[202:203], v[180:181], v[48:49], v[202:203]
	v_pk_fma_f32 v[176:177], v[52:53], v[196:197], v[198:199] op_sel_hi:[1,0,1] neg_lo:[0,1,0] neg_hi:[0,1,0]
	v_pk_fma_f32 v[180:181], v[52:53], v[196:197], v[202:203] op_sel:[0,1,0] neg_lo:[0,1,0] neg_hi:[0,1,0]
	v_pk_fma_f32 v[200:201], v[178:179], v[50:51], v[200:201]
	v_pk_fma_f32 v[204:205], v[182:183], v[50:51], v[204:205]
	v_pk_fma_f32 v[178:179], v[54:55], v[196:197], v[200:201] op_sel_hi:[1,0,1] neg_lo:[0,1,0] neg_hi:[0,1,0]
	v_pk_fma_f32 v[182:183], v[54:55], v[196:197], v[204:205] op_sel:[0,1,0] neg_lo:[0,1,0] neg_hi:[0,1,0]
	v_pk_mul_f32 v[206:207], v[176:177], v[60:61]
	v_pk_mul_f32 v[208:209], v[180:181], v[60:61]
	v_pk_fma_f32 v[206:207], v[178:179], v[62:63], v[206:207]
	v_pk_fma_f32 v[208:209], v[182:183], v[62:63], v[208:209]
	v_add_f32_e32 v210, v206, v207
	v_add_f32_e32 v211, v208, v209
	v_cndmask_b32_e64 v212, v210, v211, s[100:101]
	v_cndmask_b32_e64 v213, v211, v210, s[100:101]
	s_add_i32 s24, s24, s30
	s_nop 0
	v_add_f32_dpp v212, v213, v212 quad_perm:[1,0,3,2] row_mask:0xf bank_mask:0xf bound_ctrl:1
	s_nop 0
	s_nop 0
	v_add_f32_dpp v212, v212, v212 quad_perm:[2,3,0,1] row_mask:0xf bank_mask:0xf bound_ctrl:1
	s_nop 0
	s_nop 0
	v_add_f32_dpp v212, v212, v212 row_ror:4 row_mask:0xf bank_mask:0xf bound_ctrl:1
	s_nop 0
	s_nop 0
	v_add_f32_dpp v212, v212, v212 row_ror:8 row_mask:0xf bank_mask:0xf bound_ctrl:1
	buffer_store_dword v212, v219, s[20:23], s24 offen
	s_waitcnt vmcnt(32)
	v_pk_mul_f32 v[192:193], v[176:177], v[66:67]
	v_pk_mul_f32 v[194:195], v[180:181], v[66:67]
	v_pk_fma_f32 v[192:193], v[178:179], v[68:69], v[192:193]
	v_pk_fma_f32 v[194:195], v[182:183], v[68:69], v[194:195]
	v_add_f32_e32 v196, v192, v193
	v_add_f32_e32 v197, v194, v195
	v_pk_mul_f32 v[198:199], v[86:87], v[78:79] op_sel_hi:[0,1]
	v_add_f32_dpp v196, v196, v196 quad_perm:[1,0,3,2] row_mask:0xf bank_mask:0xf bound_ctrl:1
	v_add_f32_dpp v197, v197, v197 quad_perm:[1,0,3,2] row_mask:0xf bank_mask:0xf bound_ctrl:1
	v_pk_mul_f32 v[202:203], v[86:87], v[78:79] op_sel:[1,0]
	v_add_f32_dpp v196, v196, v196 quad_perm:[2,3,0,1] row_mask:0xf bank_mask:0xf bound_ctrl:1
	v_add_f32_dpp v197, v197, v197 quad_perm:[2,3,0,1] row_mask:0xf bank_mask:0xf bound_ctrl:1
	v_pk_mul_f32 v[200:201], v[86:87], v[80:81] op_sel_hi:[0,1]
	v_add_f32_dpp v196, v196, v196 row_ror:4 row_mask:0xf bank_mask:0xf bound_ctrl:1
	v_add_f32_dpp v197, v197, v197 row_ror:4 row_mask:0xf bank_mask:0xf bound_ctrl:1
	v_pk_mul_f32 v[204:205], v[86:87], v[80:81] op_sel:[1,0]
	v_add_f32_dpp v196, v196, v196 row_ror:8 row_mask:0xf bank_mask:0xf bound_ctrl:1
	v_add_f32_dpp v197, v197, v197 row_ror:8 row_mask:0xf bank_mask:0xf bound_ctrl:1
	v_pk_fma_f32 v[198:199], v[176:177], v[70:71], v[198:199]
	v_pk_fma_f32 v[202:203], v[180:181], v[70:71], v[202:203]
	v_pk_fma_f32 v[176:177], v[74:75], v[196:197], v[198:199] op_sel_hi:[1,0,1] neg_lo:[0,1,0] neg_hi:[0,1,0]
	v_pk_fma_f32 v[180:181], v[74:75], v[196:197], v[202:203] op_sel:[0,1,0] neg_lo:[0,1,0] neg_hi:[0,1,0]
	v_pk_fma_f32 v[200:201], v[178:179], v[72:73], v[200:201]
	v_pk_fma_f32 v[204:205], v[182:183], v[72:73], v[204:205]
	v_pk_fma_f32 v[178:179], v[76:77], v[196:197], v[200:201] op_sel_hi:[1,0,1] neg_lo:[0,1,0] neg_hi:[0,1,0]
	v_pk_fma_f32 v[182:183], v[76:77], v[196:197], v[204:205] op_sel:[0,1,0] neg_lo:[0,1,0] neg_hi:[0,1,0]
	v_pk_mul_f32 v[206:207], v[176:177], v[82:83]
	v_pk_mul_f32 v[208:209], v[180:181], v[82:83]
	v_pk_fma_f32 v[206:207], v[178:179], v[84:85], v[206:207]
	v_pk_fma_f32 v[208:209], v[182:183], v[84:85], v[208:209]
	v_add_f32_e32 v210, v206, v207
	v_add_f32_e32 v211, v208, v209
	v_cndmask_b32_e64 v212, v210, v211, s[100:101]
	v_cndmask_b32_e64 v213, v211, v210, s[100:101]
	s_add_i32 s24, s24, s30
	s_nop 0
	v_add_f32_dpp v212, v213, v212 quad_perm:[1,0,3,2] row_mask:0xf bank_mask:0xf bound_ctrl:1
	s_nop 0
	s_nop 0
	v_add_f32_dpp v212, v212, v212 quad_perm:[2,3,0,1] row_mask:0xf bank_mask:0xf bound_ctrl:1
	s_nop 0
	s_nop 0
	v_add_f32_dpp v212, v212, v212 row_ror:4 row_mask:0xf bank_mask:0xf bound_ctrl:1
	s_nop 0
	s_nop 0
	v_add_f32_dpp v212, v212, v212 row_ror:8 row_mask:0xf bank_mask:0xf bound_ctrl:1
	buffer_store_dword v212, v219, s[20:23], s24 offen
	s_waitcnt vmcnt(26)
	v_pk_mul_f32 v[192:193], v[176:177], v[88:89]
	v_pk_mul_f32 v[194:195], v[180:181], v[88:89]
	v_pk_fma_f32 v[192:193], v[178:179], v[90:91], v[192:193]
	v_pk_fma_f32 v[194:195], v[182:183], v[90:91], v[194:195]
	v_add_f32_e32 v196, v192, v193
	v_add_f32_e32 v197, v194, v195
	v_pk_mul_f32 v[198:199], v[108:109], v[100:101] op_sel_hi:[0,1]
	v_add_f32_dpp v196, v196, v196 quad_perm:[1,0,3,2] row_mask:0xf bank_mask:0xf bound_ctrl:1
	v_add_f32_dpp v197, v197, v197 quad_perm:[1,0,3,2] row_mask:0xf bank_mask:0xf bound_ctrl:1
	v_pk_mul_f32 v[202:203], v[108:109], v[100:101] op_sel:[1,0]
	v_add_f32_dpp v196, v196, v196 quad_perm:[2,3,0,1] row_mask:0xf bank_mask:0xf bound_ctrl:1
	v_add_f32_dpp v197, v197, v197 quad_perm:[2,3,0,1] row_mask:0xf bank_mask:0xf bound_ctrl:1
	v_pk_mul_f32 v[200:201], v[108:109], v[102:103] op_sel_hi:[0,1]
	v_add_f32_dpp v196, v196, v196 row_ror:4 row_mask:0xf bank_mask:0xf bound_ctrl:1
	v_add_f32_dpp v197, v197, v197 row_ror:4 row_mask:0xf bank_mask:0xf bound_ctrl:1
	v_pk_mul_f32 v[204:205], v[108:109], v[102:103] op_sel:[1,0]
	v_add_f32_dpp v196, v196, v196 row_ror:8 row_mask:0xf bank_mask:0xf bound_ctrl:1
	v_add_f32_dpp v197, v197, v197 row_ror:8 row_mask:0xf bank_mask:0xf bound_ctrl:1
	v_pk_fma_f32 v[198:199], v[176:177], v[92:93], v[198:199]
	v_pk_fma_f32 v[202:203], v[180:181], v[92:93], v[202:203]
	v_pk_fma_f32 v[176:177], v[96:97], v[196:197], v[198:199] op_sel_hi:[1,0,1] neg_lo:[0,1,0] neg_hi:[0,1,0]
	v_pk_fma_f32 v[180:181], v[96:97], v[196:197], v[202:203] op_sel:[0,1,0] neg_lo:[0,1,0] neg_hi:[0,1,0]
	v_pk_fma_f32 v[200:201], v[178:179], v[94:95], v[200:201]
	v_pk_fma_f32 v[204:205], v[182:183], v[94:95], v[204:205]
	v_pk_fma_f32 v[178:179], v[98:99], v[196:197], v[200:201] op_sel_hi:[1,0,1] neg_lo:[0,1,0] neg_hi:[0,1,0]
	v_pk_fma_f32 v[182:183], v[98:99], v[196:197], v[204:205] op_sel:[0,1,0] neg_lo:[0,1,0] neg_hi:[0,1,0]
	v_pk_mul_f32 v[206:207], v[176:177], v[104:105]
	v_pk_mul_f32 v[208:209], v[180:181], v[104:105]
	v_pk_fma_f32 v[206:207], v[178:179], v[106:107], v[206:207]
	v_pk_fma_f32 v[208:209], v[182:183], v[106:107], v[208:209]
	v_add_f32_e32 v210, v206, v207
	v_add_f32_e32 v211, v208, v209
	v_cndmask_b32_e64 v212, v210, v211, s[100:101]
	v_cndmask_b32_e64 v213, v211, v210, s[100:101]
	s_add_i32 s24, s24, s30
	s_nop 0
	v_add_f32_dpp v212, v213, v212 quad_perm:[1,0,3,2] row_mask:0xf bank_mask:0xf bound_ctrl:1
	s_nop 0
	s_nop 0
	v_add_f32_dpp v212, v212, v212 quad_perm:[2,3,0,1] row_mask:0xf bank_mask:0xf bound_ctrl:1
	s_nop 0
	s_nop 0
	v_add_f32_dpp v212, v212, v212 row_ror:4 row_mask:0xf bank_mask:0xf bound_ctrl:1
	s_nop 0
	s_nop 0
	v_add_f32_dpp v212, v212, v212 row_ror:8 row_mask:0xf bank_mask:0xf bound_ctrl:1
	buffer_store_dword v212, v219, s[20:23], s24 offen
	s_waitcnt vmcnt(20)
	v_pk_mul_f32 v[192:193], v[176:177], v[110:111]
	v_pk_mul_f32 v[194:195], v[180:181], v[110:111]
	v_pk_fma_f32 v[192:193], v[178:179], v[112:113], v[192:193]
	v_pk_fma_f32 v[194:195], v[182:183], v[112:113], v[194:195]
	v_add_f32_e32 v196, v192, v193
	v_add_f32_e32 v197, v194, v195
	v_pk_mul_f32 v[198:199], v[130:131], v[122:123] op_sel_hi:[0,1]
	v_add_f32_dpp v196, v196, v196 quad_perm:[1,0,3,2] row_mask:0xf bank_mask:0xf bound_ctrl:1
	v_add_f32_dpp v197, v197, v197 quad_perm:[1,0,3,2] row_mask:0xf bank_mask:0xf bound_ctrl:1
	v_pk_mul_f32 v[202:203], v[130:131], v[122:123] op_sel:[1,0]
	v_add_f32_dpp v196, v196, v196 quad_perm:[2,3,0,1] row_mask:0xf bank_mask:0xf bound_ctrl:1
	v_add_f32_dpp v197, v197, v197 quad_perm:[2,3,0,1] row_mask:0xf bank_mask:0xf bound_ctrl:1
	v_pk_mul_f32 v[200:201], v[130:131], v[124:125] op_sel_hi:[0,1]
	v_add_f32_dpp v196, v196, v196 row_ror:4 row_mask:0xf bank_mask:0xf bound_ctrl:1
	v_add_f32_dpp v197, v197, v197 row_ror:4 row_mask:0xf bank_mask:0xf bound_ctrl:1
	v_pk_mul_f32 v[204:205], v[130:131], v[124:125] op_sel:[1,0]
	v_add_f32_dpp v196, v196, v196 row_ror:8 row_mask:0xf bank_mask:0xf bound_ctrl:1
	v_add_f32_dpp v197, v197, v197 row_ror:8 row_mask:0xf bank_mask:0xf bound_ctrl:1
	v_pk_fma_f32 v[198:199], v[176:177], v[114:115], v[198:199]
	v_pk_fma_f32 v[202:203], v[180:181], v[114:115], v[202:203]
	v_pk_fma_f32 v[176:177], v[118:119], v[196:197], v[198:199] op_sel_hi:[1,0,1] neg_lo:[0,1,0] neg_hi:[0,1,0]
	v_pk_fma_f32 v[180:181], v[118:119], v[196:197], v[202:203] op_sel:[0,1,0] neg_lo:[0,1,0] neg_hi:[0,1,0]
	v_pk_fma_f32 v[200:201], v[178:179], v[116:117], v[200:201]
	v_pk_fma_f32 v[204:205], v[182:183], v[116:117], v[204:205]
	v_pk_fma_f32 v[178:179], v[120:121], v[196:197], v[200:201] op_sel_hi:[1,0,1] neg_lo:[0,1,0] neg_hi:[0,1,0]
	v_pk_fma_f32 v[182:183], v[120:121], v[196:197], v[204:205] op_sel:[0,1,0] neg_lo:[0,1,0] neg_hi:[0,1,0]
	v_pk_mul_f32 v[206:207], v[176:177], v[126:127]
	v_pk_mul_f32 v[208:209], v[180:181], v[126:127]
	v_pk_fma_f32 v[206:207], v[178:179], v[128:129], v[206:207]
	v_pk_fma_f32 v[208:209], v[182:183], v[128:129], v[208:209]
	v_add_f32_e32 v210, v206, v207
	v_add_f32_e32 v211, v208, v209
	v_cndmask_b32_e64 v212, v210, v211, s[100:101]
	v_cndmask_b32_e64 v213, v211, v210, s[100:101]
	s_add_i32 s24, s24, s30
	s_nop 0
	v_add_f32_dpp v212, v213, v212 quad_perm:[1,0,3,2] row_mask:0xf bank_mask:0xf bound_ctrl:1
	s_nop 0
	s_nop 0
	v_add_f32_dpp v212, v212, v212 quad_perm:[2,3,0,1] row_mask:0xf bank_mask:0xf bound_ctrl:1
	s_nop 0
	s_nop 0
	v_add_f32_dpp v212, v212, v212 row_ror:4 row_mask:0xf bank_mask:0xf bound_ctrl:1
	s_nop 0
	s_nop 0
	v_add_f32_dpp v212, v212, v212 row_ror:8 row_mask:0xf bank_mask:0xf bound_ctrl:1
	buffer_store_dword v212, v219, s[20:23], s24 offen
	s_waitcnt vmcnt(14)
	v_pk_mul_f32 v[192:193], v[176:177], v[132:133]
	v_pk_mul_f32 v[194:195], v[180:181], v[132:133]
	v_pk_fma_f32 v[192:193], v[178:179], v[134:135], v[192:193]
	v_pk_fma_f32 v[194:195], v[182:183], v[134:135], v[194:195]
	v_add_f32_e32 v196, v192, v193
	v_add_f32_e32 v197, v194, v195
	v_pk_mul_f32 v[198:199], v[152:153], v[144:145] op_sel_hi:[0,1]
	v_add_f32_dpp v196, v196, v196 quad_perm:[1,0,3,2] row_mask:0xf bank_mask:0xf bound_ctrl:1
	v_add_f32_dpp v197, v197, v197 quad_perm:[1,0,3,2] row_mask:0xf bank_mask:0xf bound_ctrl:1
	v_pk_mul_f32 v[202:203], v[152:153], v[144:145] op_sel:[1,0]
	v_add_f32_dpp v196, v196, v196 quad_perm:[2,3,0,1] row_mask:0xf bank_mask:0xf bound_ctrl:1
	v_add_f32_dpp v197, v197, v197 quad_perm:[2,3,0,1] row_mask:0xf bank_mask:0xf bound_ctrl:1
	v_pk_mul_f32 v[200:201], v[152:153], v[146:147] op_sel_hi:[0,1]
	v_add_f32_dpp v196, v196, v196 row_ror:4 row_mask:0xf bank_mask:0xf bound_ctrl:1
	v_add_f32_dpp v197, v197, v197 row_ror:4 row_mask:0xf bank_mask:0xf bound_ctrl:1
	v_pk_mul_f32 v[204:205], v[152:153], v[146:147] op_sel:[1,0]
	v_add_f32_dpp v196, v196, v196 row_ror:8 row_mask:0xf bank_mask:0xf bound_ctrl:1
	v_add_f32_dpp v197, v197, v197 row_ror:8 row_mask:0xf bank_mask:0xf bound_ctrl:1
	v_pk_fma_f32 v[198:199], v[176:177], v[136:137], v[198:199]
	v_pk_fma_f32 v[202:203], v[180:181], v[136:137], v[202:203]
	v_pk_fma_f32 v[176:177], v[140:141], v[196:197], v[198:199] op_sel_hi:[1,0,1] neg_lo:[0,1,0] neg_hi:[0,1,0]
	v_pk_fma_f32 v[180:181], v[140:141], v[196:197], v[202:203] op_sel:[0,1,0] neg_lo:[0,1,0] neg_hi:[0,1,0]
	v_pk_fma_f32 v[200:201], v[178:179], v[138:139], v[200:201]
	v_pk_fma_f32 v[204:205], v[182:183], v[138:139], v[204:205]
	v_pk_fma_f32 v[178:179], v[142:143], v[196:197], v[200:201] op_sel_hi:[1,0,1] neg_lo:[0,1,0] neg_hi:[0,1,0]
	v_pk_fma_f32 v[182:183], v[142:143], v[196:197], v[204:205] op_sel:[0,1,0] neg_lo:[0,1,0] neg_hi:[0,1,0]
	v_pk_mul_f32 v[206:207], v[176:177], v[148:149]
	v_pk_mul_f32 v[208:209], v[180:181], v[148:149]
	v_pk_fma_f32 v[206:207], v[178:179], v[150:151], v[206:207]
	v_pk_fma_f32 v[208:209], v[182:183], v[150:151], v[208:209]
	v_add_f32_e32 v210, v206, v207
	v_add_f32_e32 v211, v208, v209
	v_cndmask_b32_e64 v212, v210, v211, s[100:101]
	v_cndmask_b32_e64 v213, v211, v210, s[100:101]
	s_add_i32 s24, s24, s30
	s_nop 0
	v_add_f32_dpp v212, v213, v212 quad_perm:[1,0,3,2] row_mask:0xf bank_mask:0xf bound_ctrl:1
	s_nop 0
	s_nop 0
	v_add_f32_dpp v212, v212, v212 quad_perm:[2,3,0,1] row_mask:0xf bank_mask:0xf bound_ctrl:1
	s_nop 0
	s_nop 0
	v_add_f32_dpp v212, v212, v212 row_ror:4 row_mask:0xf bank_mask:0xf bound_ctrl:1
	s_nop 0
	s_nop 0
	v_add_f32_dpp v212, v212, v212 row_ror:8 row_mask:0xf bank_mask:0xf bound_ctrl:1
	buffer_store_dword v212, v219, s[20:23], s24 offen
	s_waitcnt vmcnt(8)
	v_pk_mul_f32 v[192:193], v[176:177], v[154:155]
	v_pk_mul_f32 v[194:195], v[180:181], v[154:155]
	v_pk_fma_f32 v[192:193], v[178:179], v[156:157], v[192:193]
	v_pk_fma_f32 v[194:195], v[182:183], v[156:157], v[194:195]
	v_add_f32_e32 v196, v192, v193
	v_add_f32_e32 v197, v194, v195
	v_pk_mul_f32 v[198:199], v[174:175], v[166:167] op_sel_hi:[0,1]
	v_add_f32_dpp v196, v196, v196 quad_perm:[1,0,3,2] row_mask:0xf bank_mask:0xf bound_ctrl:1
	v_add_f32_dpp v197, v197, v197 quad_perm:[1,0,3,2] row_mask:0xf bank_mask:0xf bound_ctrl:1
	v_pk_mul_f32 v[202:203], v[174:175], v[166:167] op_sel:[1,0]
	v_add_f32_dpp v196, v196, v196 quad_perm:[2,3,0,1] row_mask:0xf bank_mask:0xf bound_ctrl:1
	v_add_f32_dpp v197, v197, v197 quad_perm:[2,3,0,1] row_mask:0xf bank_mask:0xf bound_ctrl:1
	v_pk_mul_f32 v[200:201], v[174:175], v[168:169] op_sel_hi:[0,1]
	v_add_f32_dpp v196, v196, v196 row_ror:4 row_mask:0xf bank_mask:0xf bound_ctrl:1
	v_add_f32_dpp v197, v197, v197 row_ror:4 row_mask:0xf bank_mask:0xf bound_ctrl:1
	v_pk_mul_f32 v[204:205], v[174:175], v[168:169] op_sel:[1,0]
	v_add_f32_dpp v196, v196, v196 row_ror:8 row_mask:0xf bank_mask:0xf bound_ctrl:1
	v_add_f32_dpp v197, v197, v197 row_ror:8 row_mask:0xf bank_mask:0xf bound_ctrl:1
	v_pk_fma_f32 v[198:199], v[176:177], v[158:159], v[198:199]
	v_pk_fma_f32 v[202:203], v[180:181], v[158:159], v[202:203]
	v_pk_fma_f32 v[176:177], v[162:163], v[196:197], v[198:199] op_sel_hi:[1,0,1] neg_lo:[0,1,0] neg_hi:[0,1,0]
	v_pk_fma_f32 v[180:181], v[162:163], v[196:197], v[202:203] op_sel:[0,1,0] neg_lo:[0,1,0] neg_hi:[0,1,0]
	v_pk_fma_f32 v[200:201], v[178:179], v[160:161], v[200:201]
	v_pk_fma_f32 v[204:205], v[182:183], v[160:161], v[204:205]
	v_pk_fma_f32 v[178:179], v[164:165], v[196:197], v[200:201] op_sel_hi:[1,0,1] neg_lo:[0,1,0] neg_hi:[0,1,0]
	v_pk_fma_f32 v[182:183], v[164:165], v[196:197], v[204:205] op_sel:[0,1,0] neg_lo:[0,1,0] neg_hi:[0,1,0]
	v_pk_mul_f32 v[206:207], v[176:177], v[170:171]
	v_pk_mul_f32 v[208:209], v[180:181], v[170:171]
	v_pk_fma_f32 v[206:207], v[178:179], v[172:173], v[206:207]
	v_pk_fma_f32 v[208:209], v[182:183], v[172:173], v[208:209]
	v_add_f32_e32 v210, v206, v207
	v_add_f32_e32 v211, v208, v209
	v_cndmask_b32_e64 v212, v210, v211, s[100:101]
	v_cndmask_b32_e64 v213, v211, v210, s[100:101]
	s_add_i32 s24, s24, s30
	s_nop 0
	v_add_f32_dpp v212, v213, v212 quad_perm:[1,0,3,2] row_mask:0xf bank_mask:0xf bound_ctrl:1
	s_nop 0
	s_nop 0
	v_add_f32_dpp v212, v212, v212 quad_perm:[2,3,0,1] row_mask:0xf bank_mask:0xf bound_ctrl:1
	s_nop 0
	s_nop 0
	v_add_f32_dpp v212, v212, v212 row_ror:4 row_mask:0xf bank_mask:0xf bound_ctrl:1
	s_nop 0
	s_nop 0
	v_add_f32_dpp v212, v212, v212 row_ror:8 row_mask:0xf bank_mask:0xf bound_ctrl:1
	buffer_store_dword v212, v219, s[20:23], s24 offen
	s_add_i32 s24, s24, s30
	s_lshl_b32 s3, s94, 1
	s_add_i32 s2, s2, s3
	s_branch .Lss_item
.Lss_done:
	s_branch .LBB0_676

	.amdhsa_kernel _Z14fwd_megakernel6Params
		.amdhsa_group_segment_fixed_size 147600
		.amdhsa_private_segment_fixed_size 0
		.amdhsa_kernarg_size 600
		.amdhsa_user_sgpr_count 2
		.amdhsa_user_sgpr_dispatch_ptr 0
		.amdhsa_user_sgpr_queue_ptr 0
		.amdhsa_user_sgpr_kernarg_segment_ptr 1
		.amdhsa_user_sgpr_dispatch_id 0
		.amdhsa_user_sgpr_kernarg_preload_length 0
		.amdhsa_user_sgpr_kernarg_preload_offset 0
		.amdhsa_user_sgpr_private_segment_size 0
		.amdhsa_uses_dynamic_stack 0
		.amdhsa_enable_private_segment 0
		.amdhsa_system_sgpr_workgroup_id_x 1
		.amdhsa_system_sgpr_workgroup_id_y 0
		.amdhsa_system_sgpr_workgroup_id_z 0
		.amdhsa_system_sgpr_workgroup_info 0
		.amdhsa_system_vgpr_workitem_id 2
		.amdhsa_next_free_vgpr 242
		.amdhsa_next_free_sgpr 102
		.amdhsa_accum_offset 244
		.amdhsa_reserve_vcc 1
		.amdhsa_float_round_mode_32 0
		.amdhsa_float_round_mode_16_64 0
		.amdhsa_float_denorm_mode_32 3
		.amdhsa_float_denorm_mode_16_64 3
		.amdhsa_dx10_clamp 1
		.amdhsa_ieee_mode 1
		.amdhsa_fp16_overflow 0
		.amdhsa_tg_split 0
		.amdhsa_exception_fp_ieee_invalid_op 0
		.amdhsa_exception_fp_denorm_src 0
		.amdhsa_exception_fp_ieee_div_zero 0
		.amdhsa_exception_fp_ieee_overflow 0
		.amdhsa_exception_fp_ieee_underflow 0
		.amdhsa_exception_fp_ieee_inexact 0
		.amdhsa_exception_int_div_zero 0
	.end_amdhsa_kernel

amdhsa.kernels:
  - .agpr_count:     0
    .args:
      - .offset:         0
        .size:           344
        .value_kind:     by_value
      - .offset:         344
        .size:           4
        .value_kind:     hidden_block_count_x
      - .offset:         348
        .size:           4
        .value_kind:     hidden_block_count_y
      - .offset:         352
        .size:           4
        .value_kind:     hidden_block_count_z
      - .offset:         356
        .size:           2
        .value_kind:     hidden_group_size_x
      - .offset:         358
        .size:           2
        .value_kind:     hidden_group_size_y
      - .offset:         360
        .size:           2
        .value_kind:     hidden_group_size_z
      - .offset:         362
        .size:           2
        .value_kind:     hidden_remainder_x
      - .offset:         364
        .size:           2
        .value_kind:     hidden_remainder_y
      - .offset:         366
        .size:           2
        .value_kind:     hidden_remainder_z
      - .offset:         384
        .size:           8
        .value_kind:     hidden_global_offset_x
      - .offset:         392
        .size:           8
        .value_kind:     hidden_global_offset_y
      - .offset:         400
        .size:           8
        .value_kind:     hidden_global_offset_z
      - .offset:         408
        .size:           2
        .value_kind:     hidden_grid_dims
      - .offset:         432
        .size:           8
        .value_kind:     hidden_multigrid_sync_arg
    .group_segment_fixed_size: 147600
    .kernarg_segment_align: 8
    .kernarg_segment_size: 600
    .language:       OpenCL C
    .language_version:
      - 2
      - 0
    .max_flat_workgroup_size: 512
    .name:           _Z14fwd_megakernel6Params
    .private_segment_fixed_size: 0
    .sgpr_count:     108
    .sgpr_spill_count: 172
    .symbol:         _Z14fwd_megakernel6Params.kd
    .uniform_work_group_size: 1
    .uses_dynamic_stack: false
    .vgpr_count:     242
    .vgpr_spill_count: 0
    .wavefront_size: 64
